# second fourier FFT pass loop: same per-pass dispatch to the A0+k*S leg-address copy
# baseline (speedup 1.0000x reference)
; DI float sin_t(float turns) { return __builtin_amdgcn_sinf(__builtin_amdgcn_fractf(turns)); }
; DI float cos_t(float turns) { return __builtin_amdgcn_cosf(__builtin_amdgcn_fractf(turns)); }
; DI float2 cmul(float2 a, float2 b) { return make_float2(a.x * b.x - a.y * b.y, a.x * b.y + a.y * b.x); }
; template <int N, bool INV>
; DI void fft_lds(float2* s) {
;     ...
;     for (int lq = (LG & 1) ? LG - 3 : LG - 2; lq >= 0; lq -= 2) {
;       const int q = 1 << lq;
;       __syncthreads();
;       const float inv4q = 1.0f / (float)(4 * q);
; #pragma unroll 4
;       for (int it = 0; it < N / 4 / NT; ++it) {
;         int idx = tid + it * NT;
;         int j = idx & (q - 1), blk = idx >> lq;
;         int p0 = blk * 4 * q + j;
;         float f = (float)j * inv4q;
;         float2 t1 = make_float2(cos_t(f), -sin_t(f));
;         float2 t2 = cmul(t1, t1);
;         float2 x0 = s[phys(p0)], x1 = s[phys(p0 + q)], x2 = s[phys(p0 + 2 * q)], x3 = s[phys(p0 + 3 * q)];
;         float2 a0 = make_float2(x0.x + x2.x, x0.y + x2.y);
;         float2 a2 = cmul(make_float2(x0.x - x2.x, x0.y - x2.y), t1);
;         float2 a1 = make_float2(x1.x + x3.x, x1.y + x3.y);
;         float2 d3 = make_float2(x1.x - x3.x, x1.y - x3.y);
;         float2 a3 = cmul(make_float2(d3.y, -d3.x), t1);
;         s[phys(p0)] = make_float2(a0.x + a1.x, a0.y + a1.y);
;         s[phys(p0 + q)] = cmul(make_float2(a0.x - a1.x, a0.y - a1.y), t2);
;         s[phys(p0 + 2 * q)] = make_float2(a2.x + a3.x, a2.y + a3.y);
;         s[phys(p0 + 3 * q)] = cmul(make_float2(a2.x - a3.x, a2.y - a3.y), t2);
;       }
;     }
.LBB0_377:
	s_sub_i32 s32, s0, 4
	s_lshl_b32 s32, 0x88, s32
	s_cmp_lt_u32 s0, 4
	s_cbranch_scc0 .Lfft_fastb_377
	s_lshl_b32 s10, 4, s0
	v_cvt_f32_u32_e32 v5, s10
	s_lshl_b32 s1, 1, s0
	s_waitcnt lgkmcnt(0)
	s_barrier
	v_div_scale_f32 v6, s[10:11], v5, v5, 1.0
	v_rcp_f32_e32 v7, v6
	s_bfm_b32 s10, s0, 0
	v_and_b32_e32 v13, s10, v1
	v_fma_f32 v8, -v6, v7, 1.0
	v_fmac_f32_e32 v7, v8, v7
	v_div_scale_f32 v8, vcc, 1.0, v5, 1.0
	v_mul_f32_e32 v9, v8, v7
	v_fma_f32 v12, -v6, v9, v8
	v_fmac_f32_e32 v9, v12, v7
	v_fma_f32 v6, -v6, v9, v8
	v_div_fmas_f32 v6, v6, v7, v9
	v_div_fixup_f32 v5, v6, v5, 1.0
	v_ashrrev_i32_e32 v6, s0, v1
	v_lshlrev_b32_e32 v14, 2, v6
	v_lshl_add_u32 v15, v14, s0, v13
	v_ashrrev_i32_e32 v17, 4, v15
	v_lshlrev_b32_e32 v17, 3, v17
	v_lshlrev_b32_e32 v19, 3, v15
	v_add_u32_e32 v15, s1, v15
	v_cvt_f32_u32_e32 v6, v13
	v_add3_u32 v17, s50, v17, v19
	v_ashrrev_i32_e32 v19, 4, v15
	v_lshlrev_b32_e32 v19, 3, v19
	v_lshlrev_b32_e32 v15, 3, v15
	v_add3_u32 v19, s50, v19, v15
	v_or_b32_e32 v15, 2, v14
	v_or_b32_e32 v14, 3, v14
	v_lshl_add_u32 v15, v15, s0, v13
	v_lshl_add_u32 v13, v14, s0, v13
	v_mul_f32_e32 v6, v5, v6
	v_ashrrev_i32_e32 v20, 4, v15
	v_ashrrev_i32_e32 v14, 4, v13
	v_fract_f32_e32 v7, v6
	v_lshlrev_b32_e32 v20, 3, v20
	v_lshlrev_b32_e32 v15, 3, v15
	v_lshlrev_b32_e32 v14, 3, v14
	v_lshlrev_b32_e32 v13, 3, v13
	v_cos_f32_e32 v6, v7
	v_sin_f32_e32 v7, v7
	v_add3_u32 v23, s50, v20, v15
	v_add3_u32 v29, s50, v14, v13
	ds_read_b64 v[14:15], v17
	ds_read_b64 v[20:21], v19
	ds_read_b64 v[26:27], v23
	ds_read_b64 v[30:31], v29
	v_mov_b32_e32 v34, v7
	v_mul_f32_e64 v12, v6, -v7
	v_pk_mul_f32 v[8:9], v[6:7], v[6:7]
	s_waitcnt lgkmcnt(1)
	v_pk_add_f32 v[32:33], v[14:15], v[26:27] neg_lo:[0,1] neg_hi:[0,1]
	v_pk_add_f32 v[14:15], v[14:15], v[26:27]
	v_pk_mul_f32 v[36:37], v[34:35], v[32:33] op_sel_hi:[0,1]
	v_pk_fma_f32 v[40:41], v[6:7], v[32:33], v[36:37] op_sel:[0,0,1] op_sel_hi:[1,1,0]
	v_pk_fma_f32 v[32:33], v[6:7], v[32:33], v[36:37] op_sel:[0,0,1] op_sel_hi:[0,1,0] neg_lo:[0,0,1] neg_hi:[0,0,1]
	v_mov_b32_e32 v41, v33
	s_waitcnt lgkmcnt(0)
	v_pk_add_f32 v[32:33], v[20:21], v[30:31] neg_lo:[0,1] neg_hi:[0,1]
	v_pk_add_f32 v[20:21], v[20:21], v[30:31]
	v_add_f32_e32 v12, v12, v12
	v_pk_add_f32 v[26:27], v[14:15], v[20:21]
	v_pk_add_f32 v[14:15], v[14:15], v[20:21] neg_lo:[0,1] neg_hi:[0,1]
	v_xor_b32_e32 v37, 0x80000000, v32
	v_mov_b32_e32 v36, v33
	v_pk_mul_f32 v[32:33], v[34:35], v[32:33] op_sel_hi:[0,1]
	v_pk_mul_f32 v[20:21], v[12:13], v[14:15] op_sel_hi:[0,1]
	v_pk_add_f32 v[8:9], v[8:9], v[8:9] op_sel:[0,1] op_sel_hi:[0,1] neg_lo:[0,1] neg_hi:[0,1]
	v_pk_fma_f32 v[6:7], v[6:7], v[36:37], v[32:33] op_sel_hi:[0,1,1] neg_lo:[0,0,1] neg_hi:[0,0,1]
	ds_write_b64 v17, v[26:27]
	v_pk_fma_f32 v[26:27], v[8:9], v[14:15], v[20:21] op_sel:[0,0,1] op_sel_hi:[1,1,0] neg_lo:[0,0,1] neg_hi:[0,0,1]
	v_pk_fma_f32 v[14:15], v[8:9], v[14:15], v[20:21] op_sel:[0,0,1] op_sel_hi:[1,1,0]
	s_nop 0
	v_mov_b32_e32 v27, v15
	v_pk_add_f32 v[14:15], v[40:41], v[6:7]
	v_pk_add_f32 v[6:7], v[40:41], v[6:7] neg_lo:[0,1] neg_hi:[0,1]
	ds_write_b64 v19, v[26:27]
	v_pk_mul_f32 v[12:13], v[12:13], v[6:7] op_sel_hi:[0,1]
	ds_write_b64 v23, v[14:15]
	v_pk_fma_f32 v[14:15], v[8:9], v[6:7], v[12:13] op_sel:[0,0,1] op_sel_hi:[1,1,0] neg_lo:[0,0,1] neg_hi:[0,0,1]
	v_pk_fma_f32 v[6:7], v[8:9], v[6:7], v[12:13] op_sel:[0,0,1] op_sel_hi:[1,1,0]
	v_and_b32_e32 v13, s10, v2
	v_mov_b32_e32 v15, v7
	v_ashrrev_i32_e32 v6, s0, v2
	ds_write_b64 v29, v[14:15]
	v_lshlrev_b32_e32 v14, 2, v6
	v_lshl_add_u32 v15, v14, s0, v13
	v_ashrrev_i32_e32 v17, 4, v15
	v_lshlrev_b32_e32 v17, 3, v17
	v_lshlrev_b32_e32 v19, 3, v15
	v_add_u32_e32 v15, s1, v15
	v_cvt_f32_u32_e32 v6, v13
	v_add3_u32 v17, s50, v17, v19
	v_ashrrev_i32_e32 v19, 4, v15
	v_lshlrev_b32_e32 v19, 3, v19
	v_lshlrev_b32_e32 v15, 3, v15
	v_add3_u32 v19, s50, v19, v15
	v_or_b32_e32 v15, 2, v14
	v_or_b32_e32 v14, 3, v14
	v_lshl_add_u32 v15, v15, s0, v13
	v_lshl_add_u32 v13, v14, s0, v13
	v_mul_f32_e32 v6, v5, v6
	v_ashrrev_i32_e32 v20, 4, v15
	v_ashrrev_i32_e32 v14, 4, v13
	v_fract_f32_e32 v7, v6
	v_lshlrev_b32_e32 v20, 3, v20
	v_lshlrev_b32_e32 v15, 3, v15
	v_lshlrev_b32_e32 v14, 3, v14
	v_lshlrev_b32_e32 v13, 3, v13
	v_cos_f32_e32 v6, v7
	v_sin_f32_e32 v7, v7
	v_add3_u32 v23, s50, v20, v15
	v_add3_u32 v29, s50, v14, v13
	ds_read_b64 v[14:15], v17
	ds_read_b64 v[20:21], v19
	ds_read_b64 v[26:27], v23
	ds_read_b64 v[30:31], v29
	v_mov_b32_e32 v34, v7
	v_mul_f32_e64 v12, v6, -v7
	v_pk_mul_f32 v[8:9], v[6:7], v[6:7]
	s_waitcnt lgkmcnt(1)
	v_pk_add_f32 v[32:33], v[14:15], v[26:27] neg_lo:[0,1] neg_hi:[0,1]
	v_pk_add_f32 v[14:15], v[14:15], v[26:27]
	v_pk_mul_f32 v[36:37], v[34:35], v[32:33] op_sel_hi:[0,1]
	v_pk_fma_f32 v[40:41], v[6:7], v[32:33], v[36:37] op_sel:[0,0,1] op_sel_hi:[1,1,0]
	v_pk_fma_f32 v[32:33], v[6:7], v[32:33], v[36:37] op_sel:[0,0,1] op_sel_hi:[0,1,0] neg_lo:[0,0,1] neg_hi:[0,0,1]
	v_mov_b32_e32 v41, v33
	s_waitcnt lgkmcnt(0)
; DI float sin_t(float turns) { return __builtin_amdgcn_sinf(__builtin_amdgcn_fractf(turns)); }
; DI float cos_t(float turns) { return __builtin_amdgcn_cosf(__builtin_amdgcn_fractf(turns)); }
; DI float2 cmul(float2 a, float2 b) { return make_float2(a.x * b.x - a.y * b.y, a.x * b.y + a.y * b.x); }
; template <int N, bool INV>
; DI void fft_lds(float2* s) {
;     ...
;     for (int lq = (LG & 1) ? LG - 3 : LG - 2; lq >= 0; lq -= 2) {
;       const int q = 1 << lq;
;       __syncthreads();
;       const float inv4q = 1.0f / (float)(4 * q);
; #pragma unroll 4
;       for (int it = 0; it < N / 4 / NT; ++it) {
;         int idx = tid + it * NT;
;         int j = idx & (q - 1), blk = idx >> lq;
;         int p0 = blk * 4 * q + j;
;         float f = (float)j * inv4q;
;         float2 t1 = make_float2(cos_t(f), -sin_t(f));
;         float2 t2 = cmul(t1, t1);
;         float2 x0 = s[phys(p0)], x1 = s[phys(p0 + q)], x2 = s[phys(p0 + 2 * q)], x3 = s[phys(p0 + 3 * q)];
;         float2 a0 = make_float2(x0.x + x2.x, x0.y + x2.y);
;         float2 a2 = cmul(make_float2(x0.x - x2.x, x0.y - x2.y), t1);
;         float2 a1 = make_float2(x1.x + x3.x, x1.y + x3.y);
;         float2 d3 = make_float2(x1.x - x3.x, x1.y - x3.y);
;         float2 a3 = cmul(make_float2(d3.y, -d3.x), t1);
;         s[phys(p0)] = make_float2(a0.x + a1.x, a0.y + a1.y);
;         s[phys(p0 + q)] = cmul(make_float2(a0.x - a1.x, a0.y - a1.y), t2);
;         s[phys(p0 + 2 * q)] = make_float2(a2.x + a3.x, a2.y + a3.y);
;         s[phys(p0 + 3 * q)] = cmul(make_float2(a2.x - a3.x, a2.y - a3.y), t2);
;       }
;     }
	v_pk_add_f32 v[32:33], v[20:21], v[30:31] neg_lo:[0,1] neg_hi:[0,1]
	v_pk_add_f32 v[20:21], v[20:21], v[30:31]
	v_add_f32_e32 v12, v12, v12
	v_pk_add_f32 v[26:27], v[14:15], v[20:21]
	v_pk_add_f32 v[14:15], v[14:15], v[20:21] neg_lo:[0,1] neg_hi:[0,1]
	v_xor_b32_e32 v37, 0x80000000, v32
	v_mov_b32_e32 v36, v33
	v_pk_mul_f32 v[32:33], v[34:35], v[32:33] op_sel_hi:[0,1]
	v_pk_mul_f32 v[20:21], v[12:13], v[14:15] op_sel_hi:[0,1]
	v_pk_add_f32 v[8:9], v[8:9], v[8:9] op_sel:[0,1] op_sel_hi:[0,1] neg_lo:[0,1] neg_hi:[0,1]
	v_pk_fma_f32 v[6:7], v[6:7], v[36:37], v[32:33] op_sel_hi:[0,1,1] neg_lo:[0,0,1] neg_hi:[0,0,1]
	ds_write_b64 v17, v[26:27]
	v_pk_fma_f32 v[26:27], v[8:9], v[14:15], v[20:21] op_sel:[0,0,1] op_sel_hi:[1,1,0] neg_lo:[0,0,1] neg_hi:[0,0,1]
	v_pk_fma_f32 v[14:15], v[8:9], v[14:15], v[20:21] op_sel:[0,0,1] op_sel_hi:[1,1,0]
	s_nop 0
	v_mov_b32_e32 v27, v15
	v_pk_add_f32 v[14:15], v[40:41], v[6:7]
	v_pk_add_f32 v[6:7], v[40:41], v[6:7] neg_lo:[0,1] neg_hi:[0,1]
	ds_write_b64 v19, v[26:27]
	v_pk_mul_f32 v[12:13], v[12:13], v[6:7] op_sel_hi:[0,1]
	ds_write_b64 v23, v[14:15]
	v_pk_fma_f32 v[14:15], v[8:9], v[6:7], v[12:13] op_sel:[0,0,1] op_sel_hi:[1,1,0] neg_lo:[0,0,1] neg_hi:[0,0,1]
	v_pk_fma_f32 v[6:7], v[8:9], v[6:7], v[12:13] op_sel:[0,0,1] op_sel_hi:[1,1,0]
	v_and_b32_e32 v13, s10, v3
	v_mov_b32_e32 v15, v7
	v_ashrrev_i32_e32 v6, s0, v3
	ds_write_b64 v29, v[14:15]
	v_lshlrev_b32_e32 v14, 2, v6
	v_lshl_add_u32 v15, v14, s0, v13
	v_ashrrev_i32_e32 v17, 4, v15
	v_lshlrev_b32_e32 v17, 3, v17
	v_lshlrev_b32_e32 v19, 3, v15
	v_add_u32_e32 v15, s1, v15
	v_cvt_f32_u32_e32 v6, v13
	v_add3_u32 v17, s50, v17, v19
	v_ashrrev_i32_e32 v19, 4, v15
	v_lshlrev_b32_e32 v19, 3, v19
	v_lshlrev_b32_e32 v15, 3, v15
	v_add3_u32 v19, s50, v19, v15
	v_or_b32_e32 v15, 2, v14
	v_or_b32_e32 v14, 3, v14
	v_lshl_add_u32 v15, v15, s0, v13
	v_lshl_add_u32 v13, v14, s0, v13
	v_mul_f32_e32 v6, v5, v6
	v_ashrrev_i32_e32 v20, 4, v15
	v_ashrrev_i32_e32 v14, 4, v13
	v_fract_f32_e32 v7, v6
	v_lshlrev_b32_e32 v20, 3, v20
	v_lshlrev_b32_e32 v15, 3, v15
	v_lshlrev_b32_e32 v14, 3, v14
	v_lshlrev_b32_e32 v13, 3, v13
	v_cos_f32_e32 v6, v7
	v_sin_f32_e32 v7, v7
	v_add3_u32 v23, s50, v20, v15
	v_add3_u32 v29, s50, v14, v13
	ds_read_b64 v[14:15], v17
	ds_read_b64 v[20:21], v19
	ds_read_b64 v[26:27], v23
	ds_read_b64 v[30:31], v29
	v_mov_b32_e32 v34, v7
	v_mul_f32_e64 v12, v6, -v7
	v_pk_mul_f32 v[8:9], v[6:7], v[6:7]
	s_waitcnt lgkmcnt(1)
	v_pk_add_f32 v[32:33], v[14:15], v[26:27] neg_lo:[0,1] neg_hi:[0,1]
	v_pk_add_f32 v[14:15], v[14:15], v[26:27]
	v_pk_mul_f32 v[36:37], v[34:35], v[32:33] op_sel_hi:[0,1]
	v_pk_fma_f32 v[40:41], v[6:7], v[32:33], v[36:37] op_sel:[0,0,1] op_sel_hi:[1,1,0]
	v_pk_fma_f32 v[32:33], v[6:7], v[32:33], v[36:37] op_sel:[0,0,1] op_sel_hi:[0,1,0] neg_lo:[0,0,1] neg_hi:[0,0,1]
	v_mov_b32_e32 v41, v33
	s_waitcnt lgkmcnt(0)
	v_pk_add_f32 v[32:33], v[20:21], v[30:31] neg_lo:[0,1] neg_hi:[0,1]
	v_pk_add_f32 v[20:21], v[20:21], v[30:31]
	v_add_f32_e32 v12, v12, v12
	v_pk_add_f32 v[26:27], v[14:15], v[20:21]
	v_pk_add_f32 v[14:15], v[14:15], v[20:21] neg_lo:[0,1] neg_hi:[0,1]
	v_xor_b32_e32 v37, 0x80000000, v32
	v_mov_b32_e32 v36, v33
	v_pk_mul_f32 v[32:33], v[34:35], v[32:33] op_sel_hi:[0,1]
	v_pk_mul_f32 v[20:21], v[12:13], v[14:15] op_sel_hi:[0,1]
	v_pk_add_f32 v[8:9], v[8:9], v[8:9] op_sel:[0,1] op_sel_hi:[0,1] neg_lo:[0,1] neg_hi:[0,1]
	v_pk_fma_f32 v[6:7], v[6:7], v[36:37], v[32:33] op_sel_hi:[0,1,1] neg_lo:[0,0,1] neg_hi:[0,0,1]
	ds_write_b64 v17, v[26:27]
	v_pk_fma_f32 v[26:27], v[8:9], v[14:15], v[20:21] op_sel:[0,0,1] op_sel_hi:[1,1,0] neg_lo:[0,0,1] neg_hi:[0,0,1]
	v_pk_fma_f32 v[14:15], v[8:9], v[14:15], v[20:21] op_sel:[0,0,1] op_sel_hi:[1,1,0]
	s_nop 0
	v_mov_b32_e32 v27, v15
	v_pk_add_f32 v[14:15], v[40:41], v[6:7]
	v_pk_add_f32 v[6:7], v[40:41], v[6:7] neg_lo:[0,1] neg_hi:[0,1]
	ds_write_b64 v19, v[26:27]
	v_pk_mul_f32 v[12:13], v[12:13], v[6:7] op_sel_hi:[0,1]
	ds_write_b64 v23, v[14:15]
	v_pk_fma_f32 v[14:15], v[8:9], v[6:7], v[12:13] op_sel:[0,0,1] op_sel_hi:[1,1,0] neg_lo:[0,0,1] neg_hi:[0,0,1]
	v_pk_fma_f32 v[6:7], v[8:9], v[6:7], v[12:13] op_sel:[0,0,1] op_sel_hi:[1,1,0]
	s_nop 0
	v_and_b32_e32 v6, s10, v4
	v_cvt_f32_u32_e32 v8, v6
	v_mov_b32_e32 v15, v7
	v_ashrrev_i32_e32 v7, s0, v4
	v_lshlrev_b32_e32 v7, 2, v7
	v_mul_f32_e32 v5, v5, v8
	v_fract_f32_e32 v5, v5
	v_cos_f32_e32 v8, v5
	v_sin_f32_e32 v9, v5
	ds_write_b64 v29, v[14:15]
	v_lshl_add_u32 v15, v7, s0, v6
	v_lshlrev_b32_e32 v17, 3, v15
	v_mul_f32_e64 v5, v8, -v9
	v_add_f32_e32 v14, v5, v5
	v_ashrrev_i32_e32 v5, 4, v15
	v_lshlrev_b32_e32 v5, 3, v5
	v_add_u32_e32 v15, s1, v15
	v_add3_u32 v5, s50, v5, v17
	v_ashrrev_i32_e32 v17, 4, v15
	v_lshlrev_b32_e32 v17, 3, v17
	v_lshlrev_b32_e32 v15, 3, v15
	v_add3_u32 v15, s50, v17, v15
	v_or_b32_e32 v17, 2, v7
	v_or_b32_e32 v7, 3, v7
	v_lshl_add_u32 v17, v17, s0, v6
	v_lshl_add_u32 v6, v7, s0, v6
	v_ashrrev_i32_e32 v19, 4, v17
	v_ashrrev_i32_e32 v7, 4, v6
	v_lshlrev_b32_e32 v19, 3, v19
	v_lshlrev_b32_e32 v17, 3, v17
	v_lshlrev_b32_e32 v7, 3, v7
	v_lshlrev_b32_e32 v6, 3, v6
	v_add3_u32 v17, s50, v19, v17
	v_add3_u32 v19, s50, v7, v6
	ds_read_b64 v[6:7], v5
	ds_read_b64 v[20:21], v15
	ds_read_b64 v[26:27], v17
	ds_read_b64 v[30:31], v19
	v_mov_b32_e32 v34, v9
	v_pk_mul_f32 v[12:13], v[8:9], v[8:9]
	s_add_i32 s0, s0, -2
	s_waitcnt lgkmcnt(1)
	v_pk_add_f32 v[32:33], v[6:7], v[26:27] neg_lo:[0,1] neg_hi:[0,1]
	v_pk_add_f32 v[6:7], v[6:7], v[26:27]
	v_pk_mul_f32 v[36:37], v[34:35], v[32:33] op_sel_hi:[0,1]
	v_pk_fma_f32 v[40:41], v[8:9], v[32:33], v[36:37] op_sel:[0,0,1] op_sel_hi:[1,1,0]
	v_pk_fma_f32 v[32:33], v[8:9], v[32:33], v[36:37] op_sel:[0,0,1] op_sel_hi:[0,1,0] neg_lo:[0,0,1] neg_hi:[0,0,1]
	v_mov_b32_e32 v41, v33
	s_waitcnt lgkmcnt(0)
; DI float sin_t(float turns) { return __builtin_amdgcn_sinf(__builtin_amdgcn_fractf(turns)); }
; DI float cos_t(float turns) { return __builtin_amdgcn_cosf(__builtin_amdgcn_fractf(turns)); }
; DI float2 cmul(float2 a, float2 b) { return make_float2(a.x * b.x - a.y * b.y, a.x * b.y + a.y * b.x); }
; template <int N, bool INV>
; DI void fft_lds(float2* s) {
;     ...
;     for (int lq = (LG & 1) ? LG - 3 : LG - 2; lq >= 0; lq -= 2) {
;       const int q = 1 << lq;
;       __syncthreads();
;       const float inv4q = 1.0f / (float)(4 * q);
; #pragma unroll 4
;       for (int it = 0; it < N / 4 / NT; ++it) {
;         int idx = tid + it * NT;
;         int j = idx & (q - 1), blk = idx >> lq;
;         int p0 = blk * 4 * q + j;
;         float f = (float)j * inv4q;
;         float2 t1 = make_float2(cos_t(f), -sin_t(f));
;         float2 t2 = cmul(t1, t1);
;         float2 x0 = s[phys(p0)], x1 = s[phys(p0 + q)], x2 = s[phys(p0 + 2 * q)], x3 = s[phys(p0 + 3 * q)];
;         float2 a0 = make_float2(x0.x + x2.x, x0.y + x2.y);
;         float2 a2 = cmul(make_float2(x0.x - x2.x, x0.y - x2.y), t1);
;         float2 a1 = make_float2(x1.x + x3.x, x1.y + x3.y);
;         float2 d3 = make_float2(x1.x - x3.x, x1.y - x3.y);
;         float2 a3 = cmul(make_float2(d3.y, -d3.x), t1);
;         s[phys(p0)] = make_float2(a0.x + a1.x, a0.y + a1.y);
;         s[phys(p0 + q)] = cmul(make_float2(a0.x - a1.x, a0.y - a1.y), t2);
;         s[phys(p0 + 2 * q)] = make_float2(a2.x + a3.x, a2.y + a3.y);
;         s[phys(p0 + 3 * q)] = cmul(make_float2(a2.x - a3.x, a2.y - a3.y), t2);
;       }
;     }
	v_pk_add_f32 v[32:33], v[20:21], v[30:31] neg_lo:[0,1] neg_hi:[0,1]
	v_pk_add_f32 v[20:21], v[20:21], v[30:31]
	v_xor_b32_e32 v37, 0x80000000, v32
	v_pk_add_f32 v[26:27], v[6:7], v[20:21]
	v_pk_add_f32 v[6:7], v[6:7], v[20:21] neg_lo:[0,1] neg_hi:[0,1]
	v_mov_b32_e32 v36, v33
	v_pk_mul_f32 v[32:33], v[34:35], v[32:33] op_sel_hi:[0,1]
	v_pk_mul_f32 v[20:21], v[14:15], v[6:7] op_sel_hi:[0,1]
	v_pk_add_f32 v[12:13], v[12:13], v[12:13] op_sel:[0,1] op_sel_hi:[0,1] neg_lo:[0,1] neg_hi:[0,1]
	v_pk_fma_f32 v[8:9], v[8:9], v[36:37], v[32:33] op_sel_hi:[0,1,1] neg_lo:[0,0,1] neg_hi:[0,0,1]
	ds_write_b64 v5, v[26:27]
	v_pk_fma_f32 v[26:27], v[12:13], v[6:7], v[20:21] op_sel:[0,0,1] op_sel_hi:[1,1,0] neg_lo:[0,0,1] neg_hi:[0,0,1]
	v_pk_fma_f32 v[6:7], v[12:13], v[6:7], v[20:21] op_sel:[0,0,1] op_sel_hi:[1,1,0]
	s_cmp_lg_u32 s0, -2
	v_mov_b32_e32 v27, v7
	v_pk_add_f32 v[6:7], v[40:41], v[8:9]
	ds_write_b64 v15, v[26:27]
	ds_write_b64 v17, v[6:7]
	v_pk_add_f32 v[6:7], v[40:41], v[8:9] neg_lo:[0,1] neg_hi:[0,1]
	s_nop 0
	v_pk_mul_f32 v[8:9], v[14:15], v[6:7] op_sel_hi:[0,1]
	v_pk_fma_f32 v[14:15], v[12:13], v[6:7], v[8:9] op_sel:[0,0,1] op_sel_hi:[1,1,0] neg_lo:[0,0,1] neg_hi:[0,0,1]
	v_pk_fma_f32 v[6:7], v[12:13], v[6:7], v[8:9] op_sel:[0,0,1] op_sel_hi:[1,1,0]
	s_nop 0
	v_mov_b32_e32 v15, v7
	ds_write_b64 v19, v[14:15]
	s_cbranch_scc1 .LBB0_377
	s_branch .Lfft_doneb_377
.Lfft_fastb_377:
	s_lshl_b32 s10, 4, s0
	v_cvt_f32_u32_e32 v5, s10
	s_lshl_b32 s1, 1, s0
	s_waitcnt lgkmcnt(0)
	s_barrier
	v_div_scale_f32 v6, s[10:11], v5, v5, 1.0
	v_rcp_f32_e32 v7, v6
	s_bfm_b32 s10, s0, 0
	v_and_b32_e32 v13, s10, v1
	v_fma_f32 v8, -v6, v7, 1.0
	v_fmac_f32_e32 v7, v8, v7
	v_div_scale_f32 v8, vcc, 1.0, v5, 1.0
	v_mul_f32_e32 v9, v8, v7
	v_fma_f32 v12, -v6, v9, v8
	v_fmac_f32_e32 v9, v12, v7
	v_fma_f32 v6, -v6, v9, v8
	v_div_fmas_f32 v6, v6, v7, v9
	v_div_fixup_f32 v5, v6, v5, 1.0
	v_ashrrev_i32_e32 v6, s0, v1
	v_lshlrev_b32_e32 v14, 2, v6
	v_lshl_add_u32 v15, v14, s0, v13
	v_ashrrev_i32_e32 v17, 4, v15
	v_lshlrev_b32_e32 v17, 3, v17
	v_lshlrev_b32_e32 v19, 3, v15
	v_cvt_f32_u32_e32 v6, v13
	v_add3_u32 v17, s50, v17, v19
	v_mul_f32_e32 v6, v5, v6
	v_fract_f32_e32 v7, v6
	v_cos_f32_e32 v6, v7
	v_sin_f32_e32 v7, v7
	v_add_u32_e32 v19, s32, v17
	v_add_u32_e32 v23, s32, v19
	v_add_u32_e32 v29, s32, v23
	ds_read_b64 v[14:15], v17
	ds_read_b64 v[20:21], v19
	ds_read_b64 v[26:27], v23
	ds_read_b64 v[30:31], v29
	v_mov_b32_e32 v34, v7
	v_mul_f32_e64 v12, v6, -v7
	v_pk_mul_f32 v[8:9], v[6:7], v[6:7]
	s_waitcnt lgkmcnt(1)
	v_pk_add_f32 v[32:33], v[14:15], v[26:27] neg_lo:[0,1] neg_hi:[0,1]
	v_pk_add_f32 v[14:15], v[14:15], v[26:27]
	v_pk_mul_f32 v[36:37], v[34:35], v[32:33] op_sel_hi:[0,1]
	v_pk_fma_f32 v[40:41], v[6:7], v[32:33], v[36:37] op_sel:[0,0,1] op_sel_hi:[1,1,0]
	v_pk_fma_f32 v[32:33], v[6:7], v[32:33], v[36:37] op_sel:[0,0,1] op_sel_hi:[0,1,0] neg_lo:[0,0,1] neg_hi:[0,0,1]
	v_mov_b32_e32 v41, v33
	s_waitcnt lgkmcnt(0)
	v_pk_add_f32 v[32:33], v[20:21], v[30:31] neg_lo:[0,1] neg_hi:[0,1]
	v_pk_add_f32 v[20:21], v[20:21], v[30:31]
	v_add_f32_e32 v12, v12, v12
	v_pk_add_f32 v[26:27], v[14:15], v[20:21]
	v_pk_add_f32 v[14:15], v[14:15], v[20:21] neg_lo:[0,1] neg_hi:[0,1]
	v_xor_b32_e32 v37, 0x80000000, v32
	v_mov_b32_e32 v36, v33
	v_pk_mul_f32 v[32:33], v[34:35], v[32:33] op_sel_hi:[0,1]
	v_pk_mul_f32 v[20:21], v[12:13], v[14:15] op_sel_hi:[0,1]
	v_pk_add_f32 v[8:9], v[8:9], v[8:9] op_sel:[0,1] op_sel_hi:[0,1] neg_lo:[0,1] neg_hi:[0,1]
	v_pk_fma_f32 v[6:7], v[6:7], v[36:37], v[32:33] op_sel_hi:[0,1,1] neg_lo:[0,0,1] neg_hi:[0,0,1]
	ds_write_b64 v17, v[26:27]
	v_pk_fma_f32 v[26:27], v[8:9], v[14:15], v[20:21] op_sel:[0,0,1] op_sel_hi:[1,1,0] neg_lo:[0,0,1] neg_hi:[0,0,1]
	v_pk_fma_f32 v[14:15], v[8:9], v[14:15], v[20:21] op_sel:[0,0,1] op_sel_hi:[1,1,0]
	s_nop 0
	v_mov_b32_e32 v27, v15
	v_pk_add_f32 v[14:15], v[40:41], v[6:7]
	v_pk_add_f32 v[6:7], v[40:41], v[6:7] neg_lo:[0,1] neg_hi:[0,1]
	ds_write_b64 v19, v[26:27]
	v_pk_mul_f32 v[12:13], v[12:13], v[6:7] op_sel_hi:[0,1]
	ds_write_b64 v23, v[14:15]
	v_pk_fma_f32 v[14:15], v[8:9], v[6:7], v[12:13] op_sel:[0,0,1] op_sel_hi:[1,1,0] neg_lo:[0,0,1] neg_hi:[0,0,1]
	v_pk_fma_f32 v[6:7], v[8:9], v[6:7], v[12:13] op_sel:[0,0,1] op_sel_hi:[1,1,0]
	v_and_b32_e32 v13, s10, v2
	v_mov_b32_e32 v15, v7
	v_ashrrev_i32_e32 v6, s0, v2
	ds_write_b64 v29, v[14:15]
	v_lshlrev_b32_e32 v14, 2, v6
	v_lshl_add_u32 v15, v14, s0, v13
	v_ashrrev_i32_e32 v17, 4, v15
	v_lshlrev_b32_e32 v17, 3, v17
	v_lshlrev_b32_e32 v19, 3, v15
	v_cvt_f32_u32_e32 v6, v13
	v_add3_u32 v17, s50, v17, v19
	v_mul_f32_e32 v6, v5, v6
	v_fract_f32_e32 v7, v6
	v_cos_f32_e32 v6, v7
	v_sin_f32_e32 v7, v7
	v_add_u32_e32 v19, s32, v17
	v_add_u32_e32 v23, s32, v19
	v_add_u32_e32 v29, s32, v23
	ds_read_b64 v[14:15], v17
	ds_read_b64 v[20:21], v19
	ds_read_b64 v[26:27], v23
	ds_read_b64 v[30:31], v29
	v_mov_b32_e32 v34, v7
	v_mul_f32_e64 v12, v6, -v7
	v_pk_mul_f32 v[8:9], v[6:7], v[6:7]
	s_waitcnt lgkmcnt(1)
	v_pk_add_f32 v[32:33], v[14:15], v[26:27] neg_lo:[0,1] neg_hi:[0,1]
	v_pk_add_f32 v[14:15], v[14:15], v[26:27]
	v_pk_mul_f32 v[36:37], v[34:35], v[32:33] op_sel_hi:[0,1]
	v_pk_fma_f32 v[40:41], v[6:7], v[32:33], v[36:37] op_sel:[0,0,1] op_sel_hi:[1,1,0]
	v_pk_fma_f32 v[32:33], v[6:7], v[32:33], v[36:37] op_sel:[0,0,1] op_sel_hi:[0,1,0] neg_lo:[0,0,1] neg_hi:[0,0,1]
	v_mov_b32_e32 v41, v33
	s_waitcnt lgkmcnt(0)
; DI float sin_t(float turns) { return __builtin_amdgcn_sinf(__builtin_amdgcn_fractf(turns)); }
; DI float cos_t(float turns) { return __builtin_amdgcn_cosf(__builtin_amdgcn_fractf(turns)); }
; DI float2 cmul(float2 a, float2 b) { return make_float2(a.x * b.x - a.y * b.y, a.x * b.y + a.y * b.x); }
; template <int N, bool INV>
; DI void fft_lds(float2* s) {
;     ...
;     for (int lq = (LG & 1) ? LG - 3 : LG - 2; lq >= 0; lq -= 2) {
;       const int q = 1 << lq;
;       __syncthreads();
;       const float inv4q = 1.0f / (float)(4 * q);
; #pragma unroll 4
;       for (int it = 0; it < N / 4 / NT; ++it) {
;         int idx = tid + it * NT;
;         int j = idx & (q - 1), blk = idx >> lq;
;         int p0 = blk * 4 * q + j;
;         float f = (float)j * inv4q;
;         float2 t1 = make_float2(cos_t(f), -sin_t(f));
;         float2 t2 = cmul(t1, t1);
;         float2 x0 = s[phys(p0)], x1 = s[phys(p0 + q)], x2 = s[phys(p0 + 2 * q)], x3 = s[phys(p0 + 3 * q)];
;         float2 a0 = make_float2(x0.x + x2.x, x0.y + x2.y);
;         float2 a2 = cmul(make_float2(x0.x - x2.x, x0.y - x2.y), t1);
;         float2 a1 = make_float2(x1.x + x3.x, x1.y + x3.y);
;         float2 d3 = make_float2(x1.x - x3.x, x1.y - x3.y);
;         float2 a3 = cmul(make_float2(d3.y, -d3.x), t1);
;         s[phys(p0)] = make_float2(a0.x + a1.x, a0.y + a1.y);
;         s[phys(p0 + q)] = cmul(make_float2(a0.x - a1.x, a0.y - a1.y), t2);
;         s[phys(p0 + 2 * q)] = make_float2(a2.x + a3.x, a2.y + a3.y);
;         s[phys(p0 + 3 * q)] = cmul(make_float2(a2.x - a3.x, a2.y - a3.y), t2);
;       }
;     }
; DI void fourier_out(const float2* s, u16* FMT, int m, int tid) {
;   const float sc = 0.0013810679320049757f;
;   const int col2 = (m == 0) ? 32 : 64 - m;
; #pragma unroll
;   for (int ch = 0; ch < 2; ++ch) {
;     const int k0 = ch * 4096 + tid * 8;
;     float v[8], vm[8];
; #pragma unroll
;     for (int e = 0; e < 8; ++e) {
;       int k = k0 + e;
;       float2 zp = s[phys((int)(__brev((unsigned)k) >> 19))];
;       float2 zn = s[phys((int)(__brev((unsigned)((L - k) & (L - 1))) >> 19))];
;       if (m == 0) { v[e] = 0.5f * (zp.x + zn.x) * sc; vm[e] = 0.5f * (zp.y + zn.y) * sc; }
;       else { v[e] = zp.x * sc; vm[e] = zn.x * sc; }
	v_pk_add_f32 v[32:33], v[20:21], v[30:31] neg_lo:[0,1] neg_hi:[0,1]
	v_pk_add_f32 v[20:21], v[20:21], v[30:31]
	v_add_f32_e32 v12, v12, v12
	v_pk_add_f32 v[26:27], v[14:15], v[20:21]
	v_pk_add_f32 v[14:15], v[14:15], v[20:21] neg_lo:[0,1] neg_hi:[0,1]
	v_xor_b32_e32 v37, 0x80000000, v32
	v_mov_b32_e32 v36, v33
	v_pk_mul_f32 v[32:33], v[34:35], v[32:33] op_sel_hi:[0,1]
	v_pk_mul_f32 v[20:21], v[12:13], v[14:15] op_sel_hi:[0,1]
	v_pk_add_f32 v[8:9], v[8:9], v[8:9] op_sel:[0,1] op_sel_hi:[0,1] neg_lo:[0,1] neg_hi:[0,1]
	v_pk_fma_f32 v[6:7], v[6:7], v[36:37], v[32:33] op_sel_hi:[0,1,1] neg_lo:[0,0,1] neg_hi:[0,0,1]
	ds_write_b64 v17, v[26:27]
	v_pk_fma_f32 v[26:27], v[8:9], v[14:15], v[20:21] op_sel:[0,0,1] op_sel_hi:[1,1,0] neg_lo:[0,0,1] neg_hi:[0,0,1]
	v_pk_fma_f32 v[14:15], v[8:9], v[14:15], v[20:21] op_sel:[0,0,1] op_sel_hi:[1,1,0]
	s_nop 0
	v_mov_b32_e32 v27, v15
	v_pk_add_f32 v[14:15], v[40:41], v[6:7]
	v_pk_add_f32 v[6:7], v[40:41], v[6:7] neg_lo:[0,1] neg_hi:[0,1]
	ds_write_b64 v19, v[26:27]
	v_pk_mul_f32 v[12:13], v[12:13], v[6:7] op_sel_hi:[0,1]
	ds_write_b64 v23, v[14:15]
	v_pk_fma_f32 v[14:15], v[8:9], v[6:7], v[12:13] op_sel:[0,0,1] op_sel_hi:[1,1,0] neg_lo:[0,0,1] neg_hi:[0,0,1]
	v_pk_fma_f32 v[6:7], v[8:9], v[6:7], v[12:13] op_sel:[0,0,1] op_sel_hi:[1,1,0]
	v_and_b32_e32 v13, s10, v3
	v_mov_b32_e32 v15, v7
	v_ashrrev_i32_e32 v6, s0, v3
	ds_write_b64 v29, v[14:15]
	v_lshlrev_b32_e32 v14, 2, v6
	v_lshl_add_u32 v15, v14, s0, v13
	v_ashrrev_i32_e32 v17, 4, v15
	v_lshlrev_b32_e32 v17, 3, v17
	v_lshlrev_b32_e32 v19, 3, v15
	v_cvt_f32_u32_e32 v6, v13
	v_add3_u32 v17, s50, v17, v19
	v_mul_f32_e32 v6, v5, v6
	v_fract_f32_e32 v7, v6
	v_cos_f32_e32 v6, v7
	v_sin_f32_e32 v7, v7
	v_add_u32_e32 v19, s32, v17
	v_add_u32_e32 v23, s32, v19
	v_add_u32_e32 v29, s32, v23
	ds_read_b64 v[14:15], v17
	ds_read_b64 v[20:21], v19
	ds_read_b64 v[26:27], v23
	ds_read_b64 v[30:31], v29
	v_mov_b32_e32 v34, v7
	v_mul_f32_e64 v12, v6, -v7
	v_pk_mul_f32 v[8:9], v[6:7], v[6:7]
	s_waitcnt lgkmcnt(1)
	v_pk_add_f32 v[32:33], v[14:15], v[26:27] neg_lo:[0,1] neg_hi:[0,1]
	v_pk_add_f32 v[14:15], v[14:15], v[26:27]
	v_pk_mul_f32 v[36:37], v[34:35], v[32:33] op_sel_hi:[0,1]
	v_pk_fma_f32 v[40:41], v[6:7], v[32:33], v[36:37] op_sel:[0,0,1] op_sel_hi:[1,1,0]
	v_pk_fma_f32 v[32:33], v[6:7], v[32:33], v[36:37] op_sel:[0,0,1] op_sel_hi:[0,1,0] neg_lo:[0,0,1] neg_hi:[0,0,1]
	v_mov_b32_e32 v41, v33
	s_waitcnt lgkmcnt(0)
	v_pk_add_f32 v[32:33], v[20:21], v[30:31] neg_lo:[0,1] neg_hi:[0,1]
	v_pk_add_f32 v[20:21], v[20:21], v[30:31]
	v_add_f32_e32 v12, v12, v12
	v_pk_add_f32 v[26:27], v[14:15], v[20:21]
	v_pk_add_f32 v[14:15], v[14:15], v[20:21] neg_lo:[0,1] neg_hi:[0,1]
	v_xor_b32_e32 v37, 0x80000000, v32
	v_mov_b32_e32 v36, v33
	v_pk_mul_f32 v[32:33], v[34:35], v[32:33] op_sel_hi:[0,1]
	v_pk_mul_f32 v[20:21], v[12:13], v[14:15] op_sel_hi:[0,1]
	v_pk_add_f32 v[8:9], v[8:9], v[8:9] op_sel:[0,1] op_sel_hi:[0,1] neg_lo:[0,1] neg_hi:[0,1]
	v_pk_fma_f32 v[6:7], v[6:7], v[36:37], v[32:33] op_sel_hi:[0,1,1] neg_lo:[0,0,1] neg_hi:[0,0,1]
	ds_write_b64 v17, v[26:27]
	v_pk_fma_f32 v[26:27], v[8:9], v[14:15], v[20:21] op_sel:[0,0,1] op_sel_hi:[1,1,0] neg_lo:[0,0,1] neg_hi:[0,0,1]
	v_pk_fma_f32 v[14:15], v[8:9], v[14:15], v[20:21] op_sel:[0,0,1] op_sel_hi:[1,1,0]
	s_nop 0
	v_mov_b32_e32 v27, v15
	v_pk_add_f32 v[14:15], v[40:41], v[6:7]
	v_pk_add_f32 v[6:7], v[40:41], v[6:7] neg_lo:[0,1] neg_hi:[0,1]
	ds_write_b64 v19, v[26:27]
	v_pk_mul_f32 v[12:13], v[12:13], v[6:7] op_sel_hi:[0,1]
	ds_write_b64 v23, v[14:15]
	v_pk_fma_f32 v[14:15], v[8:9], v[6:7], v[12:13] op_sel:[0,0,1] op_sel_hi:[1,1,0] neg_lo:[0,0,1] neg_hi:[0,0,1]
	v_pk_fma_f32 v[6:7], v[8:9], v[6:7], v[12:13] op_sel:[0,0,1] op_sel_hi:[1,1,0]
	s_nop 0
	v_and_b32_e32 v6, s10, v4
	v_cvt_f32_u32_e32 v8, v6
	v_mov_b32_e32 v15, v7
	v_ashrrev_i32_e32 v7, s0, v4
	v_lshlrev_b32_e32 v7, 2, v7
	v_mul_f32_e32 v5, v5, v8
	v_fract_f32_e32 v5, v5
	v_cos_f32_e32 v8, v5
	v_sin_f32_e32 v9, v5
	ds_write_b64 v29, v[14:15]
	v_lshl_add_u32 v15, v7, s0, v6
	v_lshlrev_b32_e32 v17, 3, v15
	v_mul_f32_e64 v5, v8, -v9
	v_add_f32_e32 v14, v5, v5
	v_ashrrev_i32_e32 v5, 4, v15
	v_lshlrev_b32_e32 v5, 3, v5
	v_add3_u32 v5, s50, v5, v17
	v_add_u32_e32 v15, s32, v5
	v_add_u32_e32 v17, s32, v15
	v_add_u32_e32 v19, s32, v17
	ds_read_b64 v[6:7], v5
	ds_read_b64 v[20:21], v15
	ds_read_b64 v[26:27], v17
	ds_read_b64 v[30:31], v19
	v_mov_b32_e32 v34, v9
	v_pk_mul_f32 v[12:13], v[8:9], v[8:9]
	s_add_i32 s0, s0, -2
	s_waitcnt lgkmcnt(1)
	v_pk_add_f32 v[32:33], v[6:7], v[26:27] neg_lo:[0,1] neg_hi:[0,1]
	v_pk_add_f32 v[6:7], v[6:7], v[26:27]
	v_pk_mul_f32 v[36:37], v[34:35], v[32:33] op_sel_hi:[0,1]
	v_pk_fma_f32 v[40:41], v[8:9], v[32:33], v[36:37] op_sel:[0,0,1] op_sel_hi:[1,1,0]
	v_pk_fma_f32 v[32:33], v[8:9], v[32:33], v[36:37] op_sel:[0,0,1] op_sel_hi:[0,1,0] neg_lo:[0,0,1] neg_hi:[0,0,1]
	v_mov_b32_e32 v41, v33
	s_waitcnt lgkmcnt(0)
	v_pk_add_f32 v[32:33], v[20:21], v[30:31] neg_lo:[0,1] neg_hi:[0,1]
	v_pk_add_f32 v[20:21], v[20:21], v[30:31]
	v_xor_b32_e32 v37, 0x80000000, v32
	v_pk_add_f32 v[26:27], v[6:7], v[20:21]
	v_pk_add_f32 v[6:7], v[6:7], v[20:21] neg_lo:[0,1] neg_hi:[0,1]
	v_mov_b32_e32 v36, v33
	v_pk_mul_f32 v[32:33], v[34:35], v[32:33] op_sel_hi:[0,1]
	v_pk_mul_f32 v[20:21], v[14:15], v[6:7] op_sel_hi:[0,1]
	v_pk_add_f32 v[12:13], v[12:13], v[12:13] op_sel:[0,1] op_sel_hi:[0,1] neg_lo:[0,1] neg_hi:[0,1]
	v_pk_fma_f32 v[8:9], v[8:9], v[36:37], v[32:33] op_sel_hi:[0,1,1] neg_lo:[0,0,1] neg_hi:[0,0,1]
	ds_write_b64 v5, v[26:27]
	v_pk_fma_f32 v[26:27], v[12:13], v[6:7], v[20:21] op_sel:[0,0,1] op_sel_hi:[1,1,0] neg_lo:[0,0,1] neg_hi:[0,0,1]
	v_pk_fma_f32 v[6:7], v[12:13], v[6:7], v[20:21] op_sel:[0,0,1] op_sel_hi:[1,1,0]
	s_cmp_lg_u32 s0, -2
	v_mov_b32_e32 v27, v7
	v_pk_add_f32 v[6:7], v[40:41], v[8:9]
	ds_write_b64 v15, v[26:27]
	ds_write_b64 v17, v[6:7]
	v_pk_add_f32 v[6:7], v[40:41], v[8:9] neg_lo:[0,1] neg_hi:[0,1]
	s_nop 0
	v_pk_mul_f32 v[8:9], v[14:15], v[6:7] op_sel_hi:[0,1]
	v_pk_fma_f32 v[14:15], v[12:13], v[6:7], v[8:9] op_sel:[0,0,1] op_sel_hi:[1,1,0] neg_lo:[0,0,1] neg_hi:[0,0,1]
	v_pk_fma_f32 v[6:7], v[12:13], v[6:7], v[8:9] op_sel:[0,0,1] op_sel_hi:[1,1,0]
	s_nop 0
	v_mov_b32_e32 v15, v7
	ds_write_b64 v19, v[14:15]
	s_cbranch_scc1 .LBB0_377
.Lfft_doneb_377:
	v_bfrev_b32_e32 v1, v10
	v_lshrrev_b32_e32 v2, 19, v1
	v_lshrrev_b32_e32 v1, 23, v1
	v_add_u32_e32 v26, v1, v2
	v_sub_u32_e32 v2, 0, v10
	v_and_b32_e32 v2, 0x1ff8, v2
	v_bfrev_b32_e32 v2, v2
	v_lshrrev_b32_e32 v3, 19, v2
	v_lshrrev_b32_e32 v2, 23, v2
	v_lshl_add_u32 v1, v26, 3, 0
	v_add_u32_e32 v27, v2, v3
	s_waitcnt lgkmcnt(0)
	s_barrier
	v_lshl_add_u32 v4, v27, 3, 0
	ds_read_b32 v3, v1
	ds_read_b32 v9, v4
	s_mov_b64 s[0:1], -1
	s_and_b64 vcc, exec, s[6:7]
	s_cbranch_vccz .LBB0_380
	s_waitcnt lgkmcnt(1)
	v_mul_f32_e32 v2, 0x3ab504f3, v3
	s_mov_b64 s[0:1], 0
